# adds instruction selection in RWKV token prep: sqrt expansion + max + rcp replaced by v_rsq + v_min (20 sites)
# speedup vs baseline: 1.0609x; 1.0065x over previous
.LBB0_556:
	s_waitcnt lgkmcnt(0)
	s_barrier
	ds_read2st64_b32 v[16:17], v162 offset0:86 offset1:87
	s_and_b64 vcc, exec, s[38:39]
	s_waitcnt lgkmcnt(0)
	v_add_f32_e32 v16, 0, v16
	v_cndmask_b32_e64 v16, v16, 0, s[4:5]
	v_cndmask_b32_e64 v17, 0, v17, s[10:11]
	v_add_f32_e32 v18, v16, v17
	ds_read2st64_b32 v[16:17], v162 offset0:88 offset1:89
	s_waitcnt lgkmcnt(0)
	v_cndmask_b32_e64 v16, 0, v16, s[12:13]
	v_add_f32_e32 v16, v18, v16
	v_cndmask_b32_e64 v17, 0, v17, s[14:15]
	v_add_f32_e32 v18, v16, v17
	ds_read2st64_b32 v[16:17], v162 offset0:90 offset1:91
	s_waitcnt lgkmcnt(0)
	v_cndmask_b32_e64 v16, 0, v16, s[16:17]
	v_add_f32_e32 v16, v18, v16
	v_cndmask_b32_e64 v17, 0, v17, s[18:19]
	v_add_f32_e32 v16, v16, v17
	ds_read_b32 v17, v162 offset:23552
	s_waitcnt lgkmcnt(0)
	v_cndmask_b32_e64 v17, 0, v17, s[20:21]
	v_add_f32_e32 v16, v16, v17
	v_mov_b32_e32 v17, 0
	s_cbranch_vccnz .LBB0_558
	v_and_b32_e32 v25, 0xffff0000, v77
	v_lshlrev_b32_e32 v24, 16, v77
	v_pk_add_f32 v[28:29], v[94:95], v[24:25] neg_lo:[0,1] neg_hi:[0,1]
	v_mov_b32_e32 v27, v25
	v_fmac_f32_e32 v27, v63, v29
	v_mov_b32_e32 v30, v24
	v_mul_f32_e32 v20, v65, v27
	s_waitcnt vmcnt(0)
	v_fmac_f32_e32 v30, v69, v28
	v_mul_f32_e32 v28, v20, v20
	ds_read_b32 v19, v137 offset:13824
	v_mul_f32_e32 v18, 0xbfb8aa3b, v16
	v_mov_b32_dpp v28, v28 quad_perm:[1,0,3,2] row_mask:0xf bank_mask:0xf bound_ctrl:1
	v_fmac_f32_e32 v28, v20, v20
	v_exp_f32_e32 v18, v18
	s_waitcnt lgkmcnt(0)
	v_add_f32_e32 v16, v16, v19
	v_add_f32_dpp v28, v28, v28 quad_perm:[2,3,0,1] row_mask:0xf bank_mask:0xf bound_ctrl:1
	v_mul_f32_e32 v19, 0xbfb8aa3b, v16
	v_exp_f32_e32 v21, v19
	v_add_f32_dpp v28, v28, v28 row_ror:4 row_mask:0xf bank_mask:0xf bound_ctrl:1
	v_mul_f32_e32 v19, 0x3fb8aa3b, v16
	v_lshlrev_b32_e32 v23, 16, v73
	v_add_f32_dpp v28, v28, v28 row_ror:8 row_mask:0xf bank_mask:0xf bound_ctrl:1
	v_exp_f32_e32 v22, v19
	v_readlane_b32 s3, v28, 16
	v_readlane_b32 s40, v28, 48
	v_readlane_b32 s0, v28, 0
	v_readlane_b32 s1, v28, 32
	v_mov_b32_e32 v28, s3
	v_mov_b32_e32 v29, s40
	v_pk_add_f32 v[28:29], s[0:1], v[28:29]
	v_sub_f32_e32 v19, v135, v23
	v_add_f32_e32 v28, v28, v29
	v_fma_f32 v19, v61, v19, v23
	v_rsq_f32_e32 v28, v28
	v_lshlrev_b32_e32 v26, 16, v79
	v_mov_b32_e32 v135, v23
	v_mov_b64_e32 v[94:95], v[24:25]
	v_min_f32_e32 v28, 0x5368d4a5, v28
	s_nop 0
	v_mul_f32_e32 v28, v20, v28
	v_xor_b32_e32 v20, 0x80000000, v28
	v_pk_mul_f32 v[18:19], v[18:19], v[20:21]
	s_nop 0
	v_cvt_pk_bf16_f32 v18, v18, v19
	v_add_f32_e32 v19, -1.0, v26
	v_fma_f32 v29, v67, v19, 1.0
	v_pk_mul_f32 v[20:21], v[28:29], v[26:27]
	s_nop 0
	v_pk_mul_f32 v[20:21], v[22:23], v[20:21] op_sel_hi:[0,1]
	v_bfe_u32 v22, v30, 16, 1
	v_cvt_pk_bf16_f32 v19, v20, v21
	v_add3_u32 v22, v30, v22, s51
	v_lshrrev_b32_e32 v20, 16, v18
	v_lshrrev_b32_e32 v21, 16, v19
	v_lshrrev_b32_e32 v22, 16, v22
	s_branch .LBB0_559

.LBB0_559:
	s_and_b64 vcc, exec, s[38:39]
	ds_write_b16 v167, v18
	ds_write_b16 v167, v20 offset:2304
	ds_write_b16 v167, v19 offset:4608
	ds_write_b16 v167, v21 offset:6912
	ds_write_b16 v167, v22 offset:9216
	s_cbranch_vccnz .LBB0_561
	v_mul_f32_e32 v17, 0xbfb8aa3b, v16
	v_exp_f32_e32 v18, v17
	ds_read_b32 v17, v139 offset:13824
	v_and_b32_e32 v25, 0xffff0000, v83
	v_lshlrev_b32_e32 v24, 16, v83
	v_lshlrev_b32_e32 v23, 16, v71
	v_pk_add_f32 v[28:29], v[94:95], v[24:25] neg_lo:[0,1] neg_hi:[0,1]
	s_waitcnt lgkmcnt(0)
	v_add_f32_e32 v16, v16, v17
	v_mul_f32_e32 v17, 0xbfb8aa3b, v16
	v_exp_f32_e32 v21, v17
	v_mul_f32_e32 v17, 0x3fb8aa3b, v16
	v_mov_b32_e32 v27, v25
	v_exp_f32_e32 v22, v17
	v_sub_f32_e32 v17, v135, v23
	v_fmac_f32_e32 v27, v63, v29
	v_fma_f32 v19, v61, v17, v23
	v_mul_f32_e32 v17, v65, v27
	v_mul_f32_e32 v20, v17, v17
	v_mov_b32_e32 v30, v24
	s_waitcnt vmcnt(0)
	v_fmac_f32_e32 v30, v69, v28
	v_mov_b32_dpp v20, v20 quad_perm:[1,0,3,2] row_mask:0xf bank_mask:0xf bound_ctrl:1
	v_fmac_f32_e32 v20, v17, v17
	v_lshlrev_b32_e32 v26, 16, v85
	v_mov_b32_e32 v135, v23
	v_add_f32_dpp v20, v20, v20 quad_perm:[2,3,0,1] row_mask:0xf bank_mask:0xf bound_ctrl:1
	v_mov_b64_e32 v[94:95], v[24:25]
	s_nop 0
	v_add_f32_dpp v20, v20, v20 row_ror:4 row_mask:0xf bank_mask:0xf bound_ctrl:1
	s_nop 1
	v_add_f32_dpp v20, v20, v20 row_ror:8 row_mask:0xf bank_mask:0xf bound_ctrl:1
	s_nop 0
	v_readlane_b32 s3, v20, 16
	v_readlane_b32 s40, v20, 48
	v_readlane_b32 s0, v20, 0
	v_readlane_b32 s1, v20, 32
	v_mov_b32_e32 v28, s3
	v_mov_b32_e32 v29, s40
	v_pk_add_f32 v[28:29], s[0:1], v[28:29]
	s_nop 0
	v_add_f32_e32 v20, v28, v29
	v_rsq_f32_e32 v20, v20
	s_nop 0
	v_min_f32_e32 v20, 0x5368d4a5, v20
	s_nop 0
	v_mul_f32_e32 v28, v17, v20
	v_xor_b32_e32 v20, 0x80000000, v28
	v_pk_mul_f32 v[18:19], v[18:19], v[20:21]
	v_bfe_u32 v21, v30, 16, 1
	v_cvt_pk_bf16_f32 v17, v18, v19
	v_add_f32_e32 v18, -1.0, v26
	v_fma_f32 v29, v67, v18, 1.0
	v_pk_mul_f32 v[18:19], v[28:29], v[26:27]
	v_add3_u32 v21, v30, v21, s51
	v_pk_mul_f32 v[18:19], v[22:23], v[18:19] op_sel_hi:[0,1]
	v_cvt_pk_bf16_f32 v18, v18, v19
	v_lshrrev_b32_e32 v19, 16, v17
	v_lshrrev_b32_e32 v20, 16, v18
	v_lshrrev_b32_e32 v21, 16, v21
	s_branch .LBB0_562

.LBB0_584:
	s_waitcnt vmcnt(1)
	v_lshlrev_b32_e32 v16, 16, v89
	v_cndmask_b32_e64 v16, 0, v16, s[8:9]
	v_lshlrev_b32_e32 v17, 16, v138
	ds_write_b32 v137, v16 offset:17920
	v_add_f32_e32 v16, 0, v16
	v_cndmask_b32_e64 v17, 0, v17, s[8:9]
	v_add_f32_e32 v16, v17, v16
	ds_write_b32 v139, v17 offset:17920
	ds_write_b32 v163, v16 offset:24064
	s_waitcnt lgkmcnt(0)
	s_barrier
	ds_read2st64_b32 v[16:17], v162 offset0:94 offset1:95
	s_and_b64 vcc, exec, s[38:39]
	s_waitcnt lgkmcnt(0)
	v_add_f32_e32 v16, 0, v16
	v_cndmask_b32_e64 v16, v16, 0, s[4:5]
	v_cndmask_b32_e64 v17, 0, v17, s[10:11]
	v_add_f32_e32 v18, v16, v17
	ds_read2st64_b32 v[16:17], v162 offset0:96 offset1:97
	s_waitcnt lgkmcnt(0)
	v_cndmask_b32_e64 v16, 0, v16, s[12:13]
	v_add_f32_e32 v16, v18, v16
	v_cndmask_b32_e64 v17, 0, v17, s[14:15]
	v_add_f32_e32 v18, v16, v17
	ds_read2st64_b32 v[16:17], v162 offset0:98 offset1:99
	s_waitcnt lgkmcnt(0)
	v_cndmask_b32_e64 v16, 0, v16, s[16:17]
	v_add_f32_e32 v16, v18, v16
	v_cndmask_b32_e64 v17, 0, v17, s[18:19]
	v_add_f32_e32 v16, v16, v17
	ds_read_b32 v17, v162 offset:25600
	s_waitcnt lgkmcnt(0)
	v_cndmask_b32_e64 v17, 0, v17, s[20:21]
	v_add_f32_e32 v16, v16, v17
	v_mov_b32_e32 v17, 0
	s_cbranch_vccnz .LBB0_586
	v_and_b32_e32 v25, 0xffff0000, v133
	v_lshlrev_b32_e32 v24, 16, v133
	v_pk_add_f32 v[28:29], v[96:97], v[24:25] neg_lo:[0,1] neg_hi:[0,1]
	v_mov_b32_e32 v27, v25
	v_fmac_f32_e32 v27, v63, v29
	v_mov_b32_e32 v30, v24
	v_mul_f32_e32 v20, v65, v27
	s_waitcnt vmcnt(0)
	v_fmac_f32_e32 v30, v69, v28
	v_mul_f32_e32 v28, v20, v20
	ds_read_b32 v19, v137 offset:17920
	v_mul_f32_e32 v18, 0xbfb8aa3b, v16
	v_mov_b32_dpp v28, v28 quad_perm:[1,0,3,2] row_mask:0xf bank_mask:0xf bound_ctrl:1
	v_fmac_f32_e32 v28, v20, v20
	v_exp_f32_e32 v18, v18
	s_waitcnt lgkmcnt(0)
	v_add_f32_e32 v16, v16, v19
	v_add_f32_dpp v28, v28, v28 quad_perm:[2,3,0,1] row_mask:0xf bank_mask:0xf bound_ctrl:1
	v_mul_f32_e32 v19, 0xbfb8aa3b, v16
	v_exp_f32_e32 v21, v19
	v_add_f32_dpp v28, v28, v28 row_ror:4 row_mask:0xf bank_mask:0xf bound_ctrl:1
	v_mul_f32_e32 v19, 0x3fb8aa3b, v16
	v_lshlrev_b32_e32 v23, 16, v87
	v_add_f32_dpp v28, v28, v28 row_ror:8 row_mask:0xf bank_mask:0xf bound_ctrl:1
	v_exp_f32_e32 v22, v19
	v_readlane_b32 s3, v28, 16
	v_readlane_b32 s52, v28, 48
	v_readlane_b32 s0, v28, 0
	v_readlane_b32 s1, v28, 32
	v_mov_b32_e32 v28, s3
	v_mov_b32_e32 v29, s52
	v_pk_add_f32 v[28:29], s[0:1], v[28:29]
	v_sub_f32_e32 v19, v142, v23
	v_add_f32_e32 v28, v28, v29
	v_fma_f32 v19, v61, v19, v23
	v_rsq_f32_e32 v28, v28
	v_lshlrev_b32_e32 v26, 16, v134
	v_mov_b32_e32 v142, v23
	v_mov_b64_e32 v[96:97], v[24:25]
	v_min_f32_e32 v28, 0x5368d4a5, v28
	s_nop 0
	v_mul_f32_e32 v28, v20, v28
	v_xor_b32_e32 v20, 0x80000000, v28
	v_pk_mul_f32 v[18:19], v[18:19], v[20:21]
	s_nop 0
	v_cvt_pk_bf16_f32 v18, v18, v19
	v_add_f32_e32 v19, -1.0, v26
	v_fma_f32 v29, v67, v19, 1.0
	v_pk_mul_f32 v[20:21], v[28:29], v[26:27]
	s_nop 0
	v_pk_mul_f32 v[20:21], v[22:23], v[20:21] op_sel_hi:[0,1]
	v_bfe_u32 v22, v30, 16, 1
	v_cvt_pk_bf16_f32 v19, v20, v21
	v_add3_u32 v22, v30, v22, s51
	v_lshrrev_b32_e32 v20, 16, v18
	v_lshrrev_b32_e32 v21, 16, v19
	v_lshrrev_b32_e32 v22, 16, v22
	s_branch .LBB0_587

.LBB0_587:
	s_and_b64 vcc, exec, s[38:39]
	ds_write_b16 v167, v18
	ds_write_b16 v167, v20 offset:2304
	ds_write_b16 v167, v19 offset:4608
	ds_write_b16 v167, v21 offset:6912
	ds_write_b16 v167, v22 offset:9216
	s_cbranch_vccnz .LBB0_589
	v_mul_f32_e32 v17, 0xbfb8aa3b, v16
	v_exp_f32_e32 v18, v17
	ds_read_b32 v17, v139 offset:17920
	v_and_b32_e32 v25, 0xffff0000, v140
	v_lshlrev_b32_e32 v24, 16, v140
	v_lshlrev_b32_e32 v23, 16, v46
	v_pk_add_f32 v[28:29], v[96:97], v[24:25] neg_lo:[0,1] neg_hi:[0,1]
	s_waitcnt lgkmcnt(0)
	v_add_f32_e32 v16, v16, v17
	v_mul_f32_e32 v17, 0xbfb8aa3b, v16
	v_exp_f32_e32 v21, v17
	v_mul_f32_e32 v17, 0x3fb8aa3b, v16
	v_mov_b32_e32 v27, v25
	v_exp_f32_e32 v22, v17
	v_sub_f32_e32 v17, v142, v23
	v_fmac_f32_e32 v27, v63, v29
	v_fma_f32 v19, v61, v17, v23
	v_mul_f32_e32 v17, v65, v27
	v_mul_f32_e32 v20, v17, v17
	v_mov_b32_e32 v30, v24
	s_waitcnt vmcnt(0)
	v_fmac_f32_e32 v30, v69, v28
	v_mov_b32_dpp v20, v20 quad_perm:[1,0,3,2] row_mask:0xf bank_mask:0xf bound_ctrl:1
	v_fmac_f32_e32 v20, v17, v17
	v_lshlrev_b32_e32 v26, 16, v141
	v_mov_b32_e32 v142, v23
	v_add_f32_dpp v20, v20, v20 quad_perm:[2,3,0,1] row_mask:0xf bank_mask:0xf bound_ctrl:1
	v_mov_b64_e32 v[96:97], v[24:25]
	s_nop 0
	v_add_f32_dpp v20, v20, v20 row_ror:4 row_mask:0xf bank_mask:0xf bound_ctrl:1
	s_nop 1
	v_add_f32_dpp v20, v20, v20 row_ror:8 row_mask:0xf bank_mask:0xf bound_ctrl:1
	s_nop 0
	v_readlane_b32 s3, v20, 16
	v_readlane_b32 s52, v20, 48
	v_readlane_b32 s0, v20, 0
	v_readlane_b32 s1, v20, 32
	v_mov_b32_e32 v28, s3
	v_mov_b32_e32 v29, s52
	v_pk_add_f32 v[28:29], s[0:1], v[28:29]
	s_nop 0
	v_add_f32_e32 v20, v28, v29
	v_rsq_f32_e32 v20, v20
	s_nop 0
	v_min_f32_e32 v20, 0x5368d4a5, v20
	s_nop 0
	v_mul_f32_e32 v28, v17, v20
	v_xor_b32_e32 v20, 0x80000000, v28
	v_pk_mul_f32 v[18:19], v[18:19], v[20:21]
	v_bfe_u32 v21, v30, 16, 1
	v_cvt_pk_bf16_f32 v17, v18, v19
	v_add_f32_e32 v18, -1.0, v26
	v_fma_f32 v29, v67, v18, 1.0
	v_pk_mul_f32 v[18:19], v[28:29], v[26:27]
	v_add3_u32 v21, v30, v21, s51
	v_pk_mul_f32 v[18:19], v[22:23], v[18:19] op_sel_hi:[0,1]
	v_cvt_pk_bf16_f32 v18, v18, v19
	v_lshrrev_b32_e32 v19, 16, v17
	v_lshrrev_b32_e32 v20, 16, v18
	v_lshrrev_b32_e32 v21, 16, v21
	s_branch .LBB0_590

.LBB0_631:
	v_readlane_b32 s0, v249, 62
	s_and_b64 vcc, exec, s[44:45]
	s_nop 0
	v_add_u32_e32 v68, s0, v65
	ds_write_b32 v68, v37 offset:13824
	v_add_f32_e32 v37, 0, v37
	v_readlane_b32 s0, v248, 9
	v_add_f32_e32 v37, v37, v51
	v_add_f32_e32 v37, v37, v66
	v_add_u32_e32 v57, s0, v65
	v_readlane_b32 s0, v248, 10
	ds_write_b32 v57, v51 offset:13824
	v_add_f32_e32 v37, v37, v70
	v_add_u32_e32 v51, s0, v65
	v_readlane_b32 s0, v248, 11
	ds_write_b32 v51, v66 offset:13824
	ds_write_b32 v67, v37 offset:22016
	v_add_u32_e32 v39, s0, v65
	ds_write_b32 v39, v70 offset:13824
	s_waitcnt lgkmcnt(0)
	s_barrier
	ds_read2st64_b32 v[86:87], v65 offset0:86 offset1:87
	s_waitcnt lgkmcnt(0)
	v_add_f32_e32 v37, 0, v86
	v_cndmask_b32_e64 v37, v37, 0, s[84:85]
	v_cndmask_b32_e64 v38, 0, v87, s[40:41]
	v_add_f32_e32 v37, v37, v38
	ds_read_b32 v38, v65 offset:22528
	s_waitcnt lgkmcnt(0)
	v_cndmask_b32_e64 v38, 0, v38, s[38:39]
	v_add_f32_e32 v38, v37, v38
	s_cbranch_vccnz .LBB0_633
	ds_read_b32 v64, v68 offset:13824
	v_mul_f32_e32 v37, 0xbfb8aa3b, v38
	s_waitcnt vmcnt(0)
	v_pk_add_f32 v[32:33], v[32:33], v[30:31] neg_lo:[0,1] neg_hi:[0,1]
	v_exp_f32_e32 v86, v37
	v_fma_f32 v37, v45, v33, v31
	s_waitcnt lgkmcnt(0)
	v_add_f32_e32 v38, v38, v64
	v_mul_f32_e32 v64, v43, v37
	v_mul_f32_e32 v66, v64, v64
	v_mul_f32_e32 v33, 0xbfb8aa3b, v38
	v_exp_f32_e32 v33, v33
	v_mov_b32_dpp v66, v66 quad_perm:[1,0,3,2] row_mask:0xf bank_mask:0xf bound_ctrl:1
	v_fmac_f32_e32 v66, v64, v64
	v_sub_f32_e32 v35, v35, v29
	v_fma_f32 v87, v47, v35, v29
	v_add_f32_dpp v66, v66, v66 quad_perm:[2,3,0,1] row_mask:0xf bank_mask:0xf bound_ctrl:1
	v_fma_f32 v35, v46, v32, v30
	s_nop 0
	v_add_f32_dpp v66, v66, v66 row_ror:4 row_mask:0xf bank_mask:0xf bound_ctrl:1
	s_nop 1
	v_add_f32_dpp v66, v66, v66 row_ror:8 row_mask:0xf bank_mask:0xf bound_ctrl:1
	s_nop 0
	v_readlane_b32 s3, v66, 16
	v_readlane_b32 s51, v66, 48
	v_readlane_b32 s0, v66, 0
	v_readlane_b32 s1, v66, 32
	v_mov_b32_e32 v88, s3
	v_mov_b32_e32 v89, s51
	v_pk_add_f32 v[88:89], s[0:1], v[88:89]
	s_nop 0
	v_add_f32_e32 v66, v88, v89
	v_rsq_f32_e32 v68, v66
	v_mul_f32_e32 v66, 0x3fb8aa3b, v38
	v_exp_f32_e32 v66, v66
	v_min_f32_e32 v68, 0x5368d4a5, v68
	s_nop 0
	v_mul_f32_e32 v88, v64, v68
	v_xor_b32_e32 v32, 0x80000000, v88
	v_pk_mul_f32 v[32:33], v[86:87], v[32:33]
	s_nop 0
	v_cvt_pk_bf16_f32 v64, v32, v33
	v_add_f32_e32 v32, -1.0, v36
	v_fma_f32 v89, v42, v32, 1.0
	v_pk_mul_f32 v[32:33], v[36:37], v[88:89]
	v_lshrrev_b32_e32 v37, 16, v64
	v_pk_mul_f32 v[32:33], v[66:67], v[32:33] op_sel_hi:[0,1]
	v_cvt_pk_bf16_f32 v36, v32, v33
	v_bfe_u32 v32, v35, 16, 1
	v_add3_u32 v32, v35, v32, s81
	v_lshrrev_b32_e32 v66, 16, v36
	v_lshrrev_b32_e32 v68, 16, v32
	s_branch .LBB0_634

.LBB0_634:
	s_and_b64 vcc, exec, s[44:45]
	v_mov_b32_e32 v32, 0
	ds_write_b16 v71, v64
	ds_write_b16 v71, v37 offset:2304
	ds_write_b16 v71, v36 offset:4608
	ds_write_b16 v71, v66 offset:6912
	ds_write_b16 v71, v68 offset:9216
	s_cbranch_vccnz .LBB0_636
	ds_read_b32 v33, v57 offset:13824
	v_mul_f32_e32 v35, 0xbfb8aa3b, v38
	v_pk_add_f32 v[30:31], v[30:31], v[26:27] neg_lo:[0,1] neg_hi:[0,1]
	v_exp_f32_e32 v36, v35
	v_fma_f32 v35, v45, v31, v27
	s_waitcnt lgkmcnt(0)
	v_add_f32_e32 v38, v38, v33
	v_mul_f32_e32 v33, v43, v35
	v_mul_f32_e32 v37, v33, v33
	v_mul_f32_e32 v31, 0xbfb8aa3b, v38
	v_exp_f32_e32 v31, v31
	v_mov_b32_dpp v37, v37 quad_perm:[1,0,3,2] row_mask:0xf bank_mask:0xf bound_ctrl:1
	v_fmac_f32_e32 v37, v33, v33
	v_sub_f32_e32 v29, v29, v18
	v_mul_f32_e32 v64, 0x3fb8aa3b, v38
	v_add_f32_dpp v37, v37, v37 quad_perm:[2,3,0,1] row_mask:0xf bank_mask:0xf bound_ctrl:1
	v_exp_f32_e32 v64, v64
	s_nop 0
	v_add_f32_dpp v37, v37, v37 row_ror:4 row_mask:0xf bank_mask:0xf bound_ctrl:1
	s_nop 1
	v_add_f32_dpp v37, v37, v37 row_ror:8 row_mask:0xf bank_mask:0xf bound_ctrl:1
	s_nop 0
	v_readlane_b32 s3, v37, 16
	v_readlane_b32 s51, v37, 48
	v_readlane_b32 s0, v37, 0
	v_readlane_b32 s1, v37, 32
	v_mov_b32_e32 v86, s3
	v_mov_b32_e32 v87, s51
	v_pk_add_f32 v[86:87], s[0:1], v[86:87]
	s_nop 0
	v_add_f32_e32 v37, v86, v87
	v_rsq_f32_e32 v37, v37
	s_nop 0
	v_min_f32_e32 v57, 0x5368d4a5, v37
	v_fma_f32 v37, v47, v29, v18
	v_fma_f32 v29, v46, v30, v26
	v_mul_f32_e32 v86, v33, v57
	v_xor_b32_e32 v30, 0x80000000, v86
	v_pk_mul_f32 v[30:31], v[36:37], v[30:31]
	s_nop 0
	v_cvt_pk_bf16_f32 v33, v30, v31
	v_add_f32_e32 v30, -1.0, v34
	v_fma_f32 v87, v42, v30, 1.0
	v_pk_mul_f32 v[30:31], v[34:35], v[86:87]
	v_lshrrev_b32_e32 v35, 16, v33
	v_pk_mul_f32 v[30:31], v[64:65], v[30:31] op_sel_hi:[0,1]
	v_cvt_pk_bf16_f32 v34, v30, v31
	v_bfe_u32 v30, v29, 16, 1
	v_add3_u32 v29, v29, v30, s81
	v_lshrrev_b32_e32 v36, 16, v34
	v_lshrrev_b32_e32 v37, 16, v29
	s_branch .LBB0_637

.LBB0_637:
	s_and_b64 vcc, exec, s[44:45]
	ds_write_b16 v73, v33
	ds_write_b16 v73, v35 offset:2304
	ds_write_b16 v73, v34 offset:4608
	ds_write_b16 v73, v36 offset:6912
	ds_write_b16 v73, v37 offset:9216
	s_cbranch_vccnz .LBB0_639
	ds_read_b32 v31, v51 offset:13824
	v_mul_f32_e32 v29, 0xbfb8aa3b, v38
	v_pk_add_f32 v[26:27], v[26:27], v[24:25] neg_lo:[0,1] neg_hi:[0,1]
	v_exp_f32_e32 v30, v29
	v_fma_f32 v29, v45, v27, v25
	v_mul_f32_e32 v35, v43, v29
	s_waitcnt lgkmcnt(0)
	v_add_f32_e32 v38, v38, v31
	v_mul_f32_e32 v31, v35, v35
	v_mul_f32_e32 v27, 0xbfb8aa3b, v38
	v_exp_f32_e32 v27, v27
	v_mov_b32_dpp v31, v31 quad_perm:[1,0,3,2] row_mask:0xf bank_mask:0xf bound_ctrl:1
	v_fmac_f32_e32 v31, v35, v35
	v_sub_f32_e32 v18, v18, v49
	s_nop 0
	v_add_f32_dpp v31, v31, v31 quad_perm:[2,3,0,1] row_mask:0xf bank_mask:0xf bound_ctrl:1
	s_nop 1
	v_add_f32_dpp v31, v31, v31 row_ror:4 row_mask:0xf bank_mask:0xf bound_ctrl:1
	s_nop 1
	v_add_f32_dpp v31, v31, v31 row_ror:8 row_mask:0xf bank_mask:0xf bound_ctrl:1
	s_nop 0
	v_readlane_b32 s3, v31, 16
	v_readlane_b32 s51, v31, 48
	v_readlane_b32 s0, v31, 0
	v_readlane_b32 s1, v31, 32
	v_mov_b32_e32 v32, s3
	v_mov_b32_e32 v33, s51
	v_pk_add_f32 v[32:33], s[0:1], v[32:33]
	s_nop 0
	v_add_f32_e32 v31, v32, v33
	v_mul_f32_e32 v33, 0x3fb8aa3b, v38
	v_exp_f32_e32 v34, v33
	v_rsq_f32_e32 v31, v31
	s_nop 0
	v_min_f32_e32 v32, 0x5368d4a5, v31
	v_fma_f32 v31, v47, v18, v49
	v_fma_f32 v18, v46, v26, v24
	v_mul_f32_e32 v36, v35, v32
	v_xor_b32_e32 v26, 0x80000000, v36
	v_pk_mul_f32 v[26:27], v[30:31], v[26:27]
	s_nop 0
	v_cvt_pk_bf16_f32 v32, v26, v27
	v_add_f32_e32 v26, -1.0, v28
	v_fma_f32 v37, v42, v26, 1.0
	v_pk_mul_f32 v[26:27], v[28:29], v[36:37]
	v_lshrrev_b32_e32 v29, 16, v32
	v_pk_mul_f32 v[26:27], v[34:35], v[26:27] op_sel_hi:[0,1]
	v_cvt_pk_bf16_f32 v28, v26, v27
	v_bfe_u32 v26, v18, 16, 1
	v_add3_u32 v18, v18, v26, s81
	v_lshrrev_b32_e32 v30, 16, v28
	v_lshrrev_b32_e32 v31, 16, v18
	s_branch .LBB0_640

.LBB0_640:
	s_and_b64 vcc, exec, s[44:45]
	v_mov_b32_e32 v18, 0
	ds_write_b16 v75, v32
	ds_write_b16 v75, v29 offset:2304
	ds_write_b16 v75, v28 offset:4608
	ds_write_b16 v75, v30 offset:6912
	ds_write_b16 v75, v31 offset:9216
	s_cbranch_vccnz .LBB0_642
	ds_read_b32 v26, v39 offset:13824
	v_mul_f32_e32 v18, 0xbfb8aa3b, v38
	v_sub_f32_e32 v25, v25, v17
	v_fmac_f32_e32 v17, v45, v25
	v_sub_f32_e32 v24, v24, v20
	s_waitcnt lgkmcnt(0)
	v_add_f32_e32 v38, v38, v26
	v_mul_f32_e32 v26, 0xbfb8aa3b, v38
	v_exp_f32_e32 v27, v26
	v_mul_f32_e32 v26, 0x3fb8aa3b, v38
	v_exp_f32_e32 v28, v26
	v_sub_f32_e32 v26, v49, v19
	v_fmac_f32_e32 v19, v47, v26
	v_mul_f32_e32 v26, v43, v17
	v_fmac_f32_e32 v20, v46, v24
	v_mul_f32_e32 v24, v26, v26
	v_exp_f32_e32 v18, v18
	s_nop 0
	v_mov_b32_dpp v24, v24 quad_perm:[1,0,3,2] row_mask:0xf bank_mask:0xf bound_ctrl:1
	v_fmac_f32_e32 v24, v26, v26
	s_nop 1
	v_add_f32_dpp v24, v24, v24 quad_perm:[2,3,0,1] row_mask:0xf bank_mask:0xf bound_ctrl:1
	s_nop 1
	v_add_f32_dpp v24, v24, v24 row_ror:4 row_mask:0xf bank_mask:0xf bound_ctrl:1
	s_nop 1
	v_add_f32_dpp v24, v24, v24 row_ror:8 row_mask:0xf bank_mask:0xf bound_ctrl:1
	s_nop 0
	v_readlane_b32 s3, v24, 16
	v_readlane_b32 s44, v24, 48
	v_readlane_b32 s0, v24, 0
	v_readlane_b32 s1, v24, 32
	v_mov_b32_e32 v24, s3
	v_mov_b32_e32 v25, s44
	v_pk_add_f32 v[24:25], s[0:1], v[24:25]
	s_nop 0
	v_add_f32_e32 v24, v24, v25
	v_rsq_f32_e32 v24, v24
	s_nop 0
	v_min_f32_e32 v24, 0x5368d4a5, v24
	s_nop 0
	v_mul_f32_e32 v24, v26, v24
	v_xor_b32_e32 v26, 0x80000000, v24
	v_pk_mul_f32 v[18:19], v[18:19], v[26:27]
	s_nop 0
	v_cvt_pk_bf16_f32 v18, v18, v19
	v_add_f32_e32 v19, -1.0, v16
	v_fma_f32 v25, v42, v19, 1.0
	v_pk_mul_f32 v[16:17], v[16:17], v[24:25]
	v_bfe_u32 v24, v20, 16, 1
	v_pk_mul_f32 v[16:17], v[28:29], v[16:17] op_sel_hi:[0,1]
	v_cvt_pk_bf16_f32 v16, v16, v17
	v_add3_u32 v20, v20, v24, s81
	v_lshrrev_b32_e32 v17, 16, v18
	v_lshrrev_b32_e32 v19, 16, v16
	v_lshrrev_b32_e32 v20, 16, v20
	s_branch .LBB0_643

.LBB0_807:
	v_readlane_b32 s0, v249, 62
	s_and_b64 vcc, exec, s[44:45]
	s_nop 0
	v_add_u32_e32 v51, s0, v65
	ds_write_b32 v51, v35 offset:13824
	v_add_f32_e32 v35, 0, v35
	v_readlane_b32 s0, v248, 9
	v_add_f32_e32 v35, v35, v45
	v_add_f32_e32 v35, v35, v49
	v_add_u32_e32 v46, s0, v65
	v_readlane_b32 s0, v248, 10
	ds_write_b32 v46, v45 offset:13824
	v_add_f32_e32 v35, v35, v56
	v_add_u32_e32 v45, s0, v65
	v_readlane_b32 s0, v248, 11
	ds_write_b32 v45, v49 offset:13824
	ds_write_b32 v67, v35 offset:22016
	v_add_u32_e32 v37, s0, v65
	ds_write_b32 v37, v56 offset:13824
	s_waitcnt lgkmcnt(0)
	s_barrier
	ds_read2st64_b32 v[138:139], v65 offset0:86 offset1:87
	s_waitcnt lgkmcnt(0)
	v_add_f32_e32 v35, 0, v138
	v_cndmask_b32_e64 v35, v35, 0, s[84:85]
	v_cndmask_b32_e64 v36, 0, v139, s[40:41]
	v_add_f32_e32 v35, v35, v36
	ds_read_b32 v36, v65 offset:22528
	s_waitcnt lgkmcnt(0)
	v_cndmask_b32_e64 v36, 0, v36, s[38:39]
	v_add_f32_e32 v36, v35, v36
	s_cbranch_vccnz .LBB0_809
	ds_read_b32 v47, v51 offset:13824
	v_mul_f32_e32 v35, 0xbfb8aa3b, v36
	s_waitcnt vmcnt(0)
	v_pk_add_f32 v[32:33], v[32:33], v[30:31] neg_lo:[0,1] neg_hi:[0,1]
	v_exp_f32_e32 v138, v35
	v_fma_f32 v35, v40, v33, v31
	s_waitcnt lgkmcnt(0)
	v_add_f32_e32 v36, v36, v47
	v_mul_f32_e32 v47, v39, v35
	v_mul_f32_e32 v49, v47, v47
	v_mul_f32_e32 v33, 0xbfb8aa3b, v36
	v_exp_f32_e32 v33, v33
	v_mov_b32_dpp v49, v49 quad_perm:[1,0,3,2] row_mask:0xf bank_mask:0xf bound_ctrl:1
	v_fmac_f32_e32 v49, v47, v47
	v_sub_f32_e32 v29, v29, v25
	v_mul_f32_e32 v56, 0x3fb8aa3b, v36
	v_add_f32_dpp v49, v49, v49 quad_perm:[2,3,0,1] row_mask:0xf bank_mask:0xf bound_ctrl:1
	v_exp_f32_e32 v56, v56
	s_nop 0
	v_add_f32_dpp v49, v49, v49 row_ror:4 row_mask:0xf bank_mask:0xf bound_ctrl:1
	s_nop 1
	v_add_f32_dpp v49, v49, v49 row_ror:8 row_mask:0xf bank_mask:0xf bound_ctrl:1
	s_nop 0
	v_readlane_b32 s3, v49, 16
	v_readlane_b32 s42, v49, 48
	v_readlane_b32 s0, v49, 0
	v_readlane_b32 s1, v49, 32
	v_mov_b32_e32 v140, s3
	v_mov_b32_e32 v141, s42
	v_pk_add_f32 v[140:141], s[0:1], v[140:141]
	s_nop 0
	v_add_f32_e32 v49, v140, v141
	v_rsq_f32_e32 v49, v49
	v_fma_f32 v139, v42, v29, v25
	v_fma_f32 v29, v41, v32, v30
	v_min_f32_e32 v49, 0x5368d4a5, v49
	s_nop 0
	v_mul_f32_e32 v140, v47, v49
	v_xor_b32_e32 v32, 0x80000000, v140
	v_pk_mul_f32 v[32:33], v[138:139], v[32:33]
	s_nop 0
	v_cvt_pk_bf16_f32 v47, v32, v33
	v_add_f32_e32 v32, -1.0, v34
	v_fma_f32 v141, v38, v32, 1.0
	v_pk_mul_f32 v[32:33], v[34:35], v[140:141]
	v_lshrrev_b32_e32 v35, 16, v47
	v_pk_mul_f32 v[32:33], v[56:57], v[32:33] op_sel_hi:[0,1]
	v_cvt_pk_bf16_f32 v34, v32, v33
	v_bfe_u32 v32, v29, 16, 1
	v_add3_u32 v29, v29, v32, s94
	v_lshrrev_b32_e32 v49, 16, v34
	v_lshrrev_b32_e32 v51, 16, v29
	s_branch .LBB0_810

.LBB0_810:
	s_and_b64 vcc, exec, s[44:45]
	v_mov_b32_e32 v32, 0
	ds_write_b16 v71, v47
	ds_write_b16 v71, v35 offset:2304
	ds_write_b16 v71, v34 offset:4608
	ds_write_b16 v71, v49 offset:6912
	ds_write_b16 v71, v51 offset:9216
	s_cbranch_vccnz .LBB0_812
	ds_read_b32 v33, v46 offset:13824
	v_mul_f32_e32 v29, 0xbfb8aa3b, v36
	v_pk_add_f32 v[30:31], v[30:31], v[26:27] neg_lo:[0,1] neg_hi:[0,1]
	v_exp_f32_e32 v34, v29
	v_fma_f32 v29, v40, v31, v27
	s_waitcnt lgkmcnt(0)
	v_add_f32_e32 v36, v36, v33
	v_mul_f32_e32 v33, v39, v29
	v_mul_f32_e32 v35, v33, v33
	v_mul_f32_e32 v31, 0xbfb8aa3b, v36
	v_exp_f32_e32 v31, v31
	v_mov_b32_dpp v35, v35 quad_perm:[1,0,3,2] row_mask:0xf bank_mask:0xf bound_ctrl:1
	v_fmac_f32_e32 v35, v33, v33
	v_sub_f32_e32 v25, v25, v18
	s_nop 0
	v_add_f32_dpp v35, v35, v35 quad_perm:[2,3,0,1] row_mask:0xf bank_mask:0xf bound_ctrl:1
	s_nop 1
	v_add_f32_dpp v35, v35, v35 row_ror:4 row_mask:0xf bank_mask:0xf bound_ctrl:1
	s_nop 1
	v_add_f32_dpp v35, v35, v35 row_ror:8 row_mask:0xf bank_mask:0xf bound_ctrl:1
	s_nop 0
	v_readlane_b32 s3, v35, 16
	v_readlane_b32 s42, v35, 48
	v_readlane_b32 s0, v35, 0
	v_readlane_b32 s1, v35, 32
	v_mov_b32_e32 v46, s3
	v_mov_b32_e32 v47, s42
	v_pk_add_f32 v[46:47], s[0:1], v[46:47]
	s_nop 0
	v_add_f32_e32 v35, v46, v47
	v_rsq_f32_e32 v35, v35
	v_mul_f32_e32 v46, 0x3fb8aa3b, v36
	v_exp_f32_e32 v46, v46
	v_min_f32_e32 v47, 0x5368d4a5, v35
	v_fma_f32 v35, v42, v25, v18
	v_fma_f32 v25, v41, v30, v26
	v_mul_f32_e32 v138, v33, v47
	v_xor_b32_e32 v30, 0x80000000, v138
	v_pk_mul_f32 v[30:31], v[34:35], v[30:31]
	s_nop 0
	v_cvt_pk_bf16_f32 v33, v30, v31
	v_add_f32_e32 v30, -1.0, v28
	v_fma_f32 v139, v38, v30, 1.0
	v_pk_mul_f32 v[28:29], v[28:29], v[138:139]
	v_bfe_u32 v30, v25, 16, 1
	v_pk_mul_f32 v[28:29], v[46:47], v[28:29] op_sel_hi:[0,1]
	v_cvt_pk_bf16_f32 v28, v28, v29
	v_add3_u32 v25, v25, v30, s94
	v_lshrrev_b32_e32 v29, 16, v33
	v_lshrrev_b32_e32 v34, 16, v28
	v_lshrrev_b32_e32 v35, 16, v25
	s_branch .LBB0_813

.LBB0_813:
	s_and_b64 vcc, exec, s[44:45]
	ds_write_b16 v73, v33
	ds_write_b16 v73, v29 offset:2304
	ds_write_b16 v73, v28 offset:4608
	ds_write_b16 v73, v34 offset:6912
	ds_write_b16 v73, v35 offset:9216
	s_cbranch_vccnz .LBB0_815
	ds_read_b32 v29, v45 offset:13824
	v_mul_f32_e32 v25, 0xbfb8aa3b, v36
	v_pk_add_f32 v[26:27], v[26:27], v[22:23] neg_lo:[0,1] neg_hi:[0,1]
	v_exp_f32_e32 v28, v25
	v_fma_f32 v25, v40, v27, v23
	v_mul_f32_e32 v32, v39, v25
	s_waitcnt lgkmcnt(0)
	v_add_f32_e32 v36, v36, v29
	v_mul_f32_e32 v29, v32, v32
	v_mul_f32_e32 v27, 0xbfb8aa3b, v36
	v_exp_f32_e32 v27, v27
	v_mov_b32_dpp v29, v29 quad_perm:[1,0,3,2] row_mask:0xf bank_mask:0xf bound_ctrl:1
	v_fmac_f32_e32 v29, v32, v32
	v_sub_f32_e32 v18, v18, v44
	s_nop 0
	v_add_f32_dpp v29, v29, v29 quad_perm:[2,3,0,1] row_mask:0xf bank_mask:0xf bound_ctrl:1
	s_nop 1
	v_add_f32_dpp v29, v29, v29 row_ror:4 row_mask:0xf bank_mask:0xf bound_ctrl:1
	s_nop 1
	v_add_f32_dpp v29, v29, v29 row_ror:8 row_mask:0xf bank_mask:0xf bound_ctrl:1
	s_nop 0
	v_readlane_b32 s3, v29, 16
	v_readlane_b32 s42, v29, 48
	v_readlane_b32 s0, v29, 0
	v_readlane_b32 s1, v29, 32
	v_mov_b32_e32 v30, s3
	v_mov_b32_e32 v31, s42
	v_pk_add_f32 v[30:31], s[0:1], v[30:31]
	s_nop 0
	v_add_f32_e32 v29, v30, v31
	v_rsq_f32_e32 v29, v29
	v_mul_f32_e32 v30, 0x3fb8aa3b, v36
	v_exp_f32_e32 v30, v30
	v_min_f32_e32 v31, 0x5368d4a5, v29
	v_fma_f32 v29, v42, v18, v44
	v_fma_f32 v18, v41, v26, v22
	v_mul_f32_e32 v34, v32, v31
	v_xor_b32_e32 v26, 0x80000000, v34
	v_pk_mul_f32 v[26:27], v[28:29], v[26:27]
	s_nop 0
	v_cvt_pk_bf16_f32 v32, v26, v27
	v_add_f32_e32 v26, -1.0, v24
	v_fma_f32 v35, v38, v26, 1.0
	v_pk_mul_f32 v[24:25], v[24:25], v[34:35]
	v_bfe_u32 v26, v18, 16, 1
	v_pk_mul_f32 v[24:25], v[30:31], v[24:25] op_sel_hi:[0,1]
	v_cvt_pk_bf16_f32 v24, v24, v25
	v_add3_u32 v18, v18, v26, s94
	v_lshrrev_b32_e32 v25, 16, v32
	v_lshrrev_b32_e32 v28, 16, v24
	v_lshrrev_b32_e32 v29, 16, v18
	s_branch .LBB0_816

.LBB0_816:
	s_and_b64 vcc, exec, s[44:45]
	v_mov_b32_e32 v18, 0
	ds_write_b16 v75, v32
	ds_write_b16 v75, v25 offset:2304
	ds_write_b16 v75, v24 offset:4608
	ds_write_b16 v75, v28 offset:6912
	ds_write_b16 v75, v29 offset:9216
	s_cbranch_vccnz .LBB0_818
	ds_read_b32 v24, v37 offset:13824
	v_mul_f32_e32 v18, 0xbfb8aa3b, v36
	v_sub_f32_e32 v23, v23, v17
	v_fmac_f32_e32 v17, v40, v23
	v_sub_f32_e32 v22, v22, v43
	s_waitcnt lgkmcnt(0)
	v_add_f32_e32 v36, v36, v24
	v_mul_f32_e32 v24, 0xbfb8aa3b, v36
	v_exp_f32_e32 v25, v24
	v_mul_f32_e32 v24, 0x3fb8aa3b, v36
	v_exp_f32_e32 v26, v24
	v_sub_f32_e32 v24, v44, v19
	v_fmac_f32_e32 v19, v42, v24
	v_mul_f32_e32 v24, v39, v17
	v_fmac_f32_e32 v43, v41, v22
	v_mul_f32_e32 v22, v24, v24
	v_exp_f32_e32 v18, v18
	s_nop 0
	v_mov_b32_dpp v22, v22 quad_perm:[1,0,3,2] row_mask:0xf bank_mask:0xf bound_ctrl:1
	v_fmac_f32_e32 v22, v24, v24
	s_nop 1
	v_add_f32_dpp v22, v22, v22 quad_perm:[2,3,0,1] row_mask:0xf bank_mask:0xf bound_ctrl:1
	s_nop 1
	v_add_f32_dpp v22, v22, v22 row_ror:4 row_mask:0xf bank_mask:0xf bound_ctrl:1
	s_nop 1
	v_add_f32_dpp v22, v22, v22 row_ror:8 row_mask:0xf bank_mask:0xf bound_ctrl:1
	s_nop 0
	v_readlane_b32 s3, v22, 16
	v_readlane_b32 s42, v22, 48
	v_readlane_b32 s0, v22, 0
	v_readlane_b32 s1, v22, 32
	v_mov_b32_e32 v22, s3
	v_mov_b32_e32 v23, s42
	v_pk_add_f32 v[22:23], s[0:1], v[22:23]
	s_nop 0
	v_add_f32_e32 v22, v22, v23
	v_rsq_f32_e32 v22, v22
	s_nop 0
	v_min_f32_e32 v22, 0x5368d4a5, v22
	s_nop 0
	v_mul_f32_e32 v22, v24, v22
	v_xor_b32_e32 v24, 0x80000000, v22
	v_pk_mul_f32 v[18:19], v[18:19], v[24:25]
	s_nop 0
	v_cvt_pk_bf16_f32 v18, v18, v19
	v_add_f32_e32 v19, -1.0, v16
	v_fma_f32 v23, v38, v19, 1.0
	v_pk_mul_f32 v[16:17], v[16:17], v[22:23]
	v_bfe_u32 v22, v43, 16, 1
	v_pk_mul_f32 v[16:17], v[26:27], v[16:17] op_sel_hi:[0,1]
	v_cvt_pk_bf16_f32 v16, v16, v17
	v_add3_u32 v22, v43, v22, s94
	v_lshrrev_b32_e32 v17, 16, v18
	v_lshrrev_b32_e32 v19, 16, v16
	v_lshrrev_b32_e32 v22, 16, v22
	s_branch .LBB0_819

.LBB0_841:
	s_waitcnt lgkmcnt(0)
	s_barrier
	ds_read2st64_b32 v[16:17], v65 offset0:86 offset1:87
	ds_read_b32 v18, v65 offset:22528
	ds_read_b32 v19, v203 offset:13824
	ds_read_b32 v21, v204 offset:13824
	ds_read_b32 v26, v207 offset:13824
	ds_read_b32 v27, v211 offset:13824
	s_waitcnt lgkmcnt(5)
	v_add_f32_e32 v16, 0, v16
	v_cndmask_b32_e64 v16, v16, 0, s[84:85]
	v_cndmask_b32_e64 v17, 0, v17, s[40:41]
	v_add_f32_e32 v16, v16, v17
	s_waitcnt lgkmcnt(4)
	v_cndmask_b32_e64 v17, 0, v18, s[38:39]
	v_add_f32_e32 v17, v16, v17
	s_waitcnt lgkmcnt(3)
	v_add_f32_e32 v28, v19, v17
	v_mul_f32_e32 v16, 0xbfb8aa3b, v17
	v_mul_f32_e32 v17, 0xbfb8aa3b, v28
	v_exp_f32_e32 v19, v17
	v_mul_f32_e32 v17, 0x3fb8aa3b, v28
	v_lshlrev_b32_e32 v30, 16, v157
	v_exp_f32_e32 v20, v17
	v_sub_f32_e32 v17, v145, v30
	v_fma_f32 v23, v139, v17, v30
	v_mul_f32_e32 v18, v154, v23
	v_mul_f32_e32 v17, v18, v18
	v_exp_f32_e32 v16, v16
	v_lshlrev_b32_e32 v29, 16, v147
	v_mov_b32_dpp v17, v17 quad_perm:[1,0,3,2] row_mask:0xf bank_mask:0xf bound_ctrl:1
	v_fmac_f32_e32 v17, v18, v18
	v_lshlrev_b32_e32 v31, 16, v174
	s_waitcnt lgkmcnt(2)
	v_add_f32_e32 v28, v28, v21
	v_add_f32_dpp v17, v17, v17 quad_perm:[2,3,0,1] row_mask:0xf bank_mask:0xf bound_ctrl:1
	s_waitcnt lgkmcnt(1)
	v_add_f32_e32 v26, v28, v26
	v_and_b32_e32 v145, 0xffff0000, v221
	v_add_f32_dpp v17, v17, v17 row_ror:4 row_mask:0xf bank_mask:0xf bound_ctrl:1
	s_nop 1
	v_add_f32_dpp v17, v17, v17 row_ror:8 row_mask:0xf bank_mask:0xf bound_ctrl:1
	s_nop 0
	v_readlane_b32 s3, v17, 16
	v_readlane_b32 s43, v17, 48
	v_readlane_b32 s0, v17, 0
	v_readlane_b32 s1, v17, 32
	v_mov_b32_e32 v24, s3
	v_mov_b32_e32 v25, s43
	v_pk_add_f32 v[24:25], s[0:1], v[24:25]
	s_nop 0
	v_add_f32_e32 v17, v24, v25
	v_sub_f32_e32 v25, v146, v29
	v_lshlrev_b32_e32 v146, 16, v195
	v_rsq_f32_e32 v17, v17
	v_lshlrev_b32_e32 v22, 16, v177
	v_lshlrev_b32_e32 v33, 16, v183
	s_nop 0
	v_min_f32_e32 v24, 0x5368d4a5, v17
	v_fma_f32 v17, v51, v25, v29
	v_sub_f32_e32 v25, v144, v31
	v_fma_f32 v32, v156, v25, v31
	v_mul_f32_e32 v24, v18, v24
	v_xor_b32_e32 v18, 0x80000000, v24
	v_pk_mul_f32 v[16:17], v[16:17], v[18:19]
	v_lshlrev_b32_e32 v144, 16, v221
	v_cvt_pk_bf16_f32 v18, v16, v17
	v_add_f32_e32 v16, -1.0, v22
	v_fma_f32 v25, v155, v16, 1.0
	v_pk_mul_f32 v[16:17], v[24:25], v[22:23]
	s_nop 0
	v_pk_mul_f32 v[16:17], v[20:21], v[16:17] op_sel_hi:[0,1]
	v_cvt_pk_bf16_f32 v16, v16, v17
	ds_write_b16 v71, v18
	ds_write_b16_d16_hi v71, v18 offset:2304
	ds_write_b16 v71, v16 offset:4608
	ds_write_b16_d16_hi v71, v16 offset:6912
	v_bfe_u32 v16, v32, 16, 1
	v_add3_u32 v16, v32, v16, s94
	ds_write_b16_d16_hi v71, v16 offset:9216
	v_mul_f32_e32 v16, 0xbfb8aa3b, v28
	v_exp_f32_e32 v17, v16
	v_mul_f32_e32 v16, 0x3fb8aa3b, v28
	v_exp_f32_e32 v18, v16
	v_sub_f32_e32 v16, v30, v33
	v_fma_f32 v21, v139, v16, v33
	v_mul_f32_e32 v16, v154, v21
	v_mul_f32_e32 v20, v16, v16
	v_lshlrev_b32_e32 v32, 16, v181
	v_sub_f32_e32 v24, v29, v32
	v_mov_b32_dpp v20, v20 quad_perm:[1,0,3,2] row_mask:0xf bank_mask:0xf bound_ctrl:1
	v_fmac_f32_e32 v20, v16, v16
	v_lshlrev_b32_e32 v30, 16, v184
	v_lshlrev_b32_e32 v28, 16, v187
	v_add_f32_dpp v20, v20, v20 quad_perm:[2,3,0,1] row_mask:0xf bank_mask:0xf bound_ctrl:1
	s_nop 1
	v_add_f32_dpp v20, v20, v20 row_ror:4 row_mask:0xf bank_mask:0xf bound_ctrl:1
	s_nop 1
	v_add_f32_dpp v20, v20, v20 row_ror:8 row_mask:0xf bank_mask:0xf bound_ctrl:1
	s_nop 0
	v_readlane_b32 s3, v20, 16
	v_readlane_b32 s43, v20, 48
	v_readlane_b32 s0, v20, 0
	v_readlane_b32 s1, v20, 32
	v_mov_b32_e32 v22, s3
	v_mov_b32_e32 v23, s43
	v_pk_add_f32 v[22:23], s[0:1], v[22:23]
	s_nop 0
	v_add_f32_e32 v20, v22, v23
	v_rsq_f32_e32 v22, v20
	v_lshlrev_b32_e32 v20, 16, v186
	v_min_f32_e32 v22, 0x5368d4a5, v22
	v_fma_f32 v23, v51, v24, v32
	v_sub_f32_e32 v24, v31, v30
	v_fma_f32 v29, v156, v24, v30
	v_mul_f32_e32 v24, v16, v22
	v_mov_b32_e32 v22, v19
	v_add_f32_e32 v19, -1.0, v20
	v_xor_b32_e32 v16, 0x80000000, v24
	v_fma_f32 v25, v155, v19, 1.0
	v_pk_mul_f32 v[22:23], v[22:23], v[16:17]
	v_pk_mul_f32 v[20:21], v[24:25], v[20:21]
	v_cvt_pk_bf16_f32 v16, v22, v23
	v_pk_mul_f32 v[18:19], v[18:19], v[20:21] op_sel_hi:[0,1]
	v_cvt_pk_bf16_f32 v18, v18, v19
	ds_write_b16 v73, v16
	ds_write_b16_d16_hi v73, v16 offset:2304
	ds_write_b16 v73, v18 offset:4608
	ds_write_b16_d16_hi v73, v18 offset:6912
	v_bfe_u32 v16, v29, 16, 1
	v_add3_u32 v16, v29, v16, s94
	v_lshlrev_b32_e32 v29, 16, v188
	v_sub_f32_e32 v18, v33, v29
	v_fma_f32 v21, v139, v18, v29
	v_mul_f32_e32 v18, v154, v21
	v_mul_f32_e32 v20, v18, v18
	v_sub_f32_e32 v24, v32, v28
	ds_write_b16_d16_hi v73, v16 offset:9216
	v_mov_b32_dpp v20, v20 quad_perm:[1,0,3,2] row_mask:0xf bank_mask:0xf bound_ctrl:1
	v_fmac_f32_e32 v20, v18, v18
	v_mul_f32_e32 v16, 0xbfb8aa3b, v26
	v_exp_f32_e32 v19, v16
	v_add_f32_dpp v20, v20, v20 quad_perm:[2,3,0,1] row_mask:0xf bank_mask:0xf bound_ctrl:1
	v_mul_f32_e32 v16, 0x3fb8aa3b, v26
	v_lshlrev_b32_e32 v31, 16, v189
	v_add_f32_dpp v20, v20, v20 row_ror:4 row_mask:0xf bank_mask:0xf bound_ctrl:1
	v_exp_f32_e32 v16, v16
	s_nop 0
	v_add_f32_dpp v20, v20, v20 row_ror:8 row_mask:0xf bank_mask:0xf bound_ctrl:1
	s_nop 0
	v_readlane_b32 s3, v20, 16
	v_readlane_b32 s43, v20, 48
	v_readlane_b32 s0, v20, 0
	v_readlane_b32 s1, v20, 32
	v_mov_b32_e32 v22, s3
	v_mov_b32_e32 v23, s43
	v_pk_add_f32 v[22:23], s[0:1], v[22:23]
	s_nop 0
	v_add_f32_e32 v20, v22, v23
	v_rsq_f32_e32 v22, v20
	v_lshlrev_b32_e32 v20, 16, v194
	v_min_f32_e32 v22, 0x5368d4a5, v22
	v_fma_f32 v23, v51, v24, v28
	v_sub_f32_e32 v24, v30, v31
	v_fma_f32 v30, v156, v24, v31
	v_mul_f32_e32 v24, v18, v22
	v_mov_b32_e32 v22, v17
	v_add_f32_e32 v17, -1.0, v20
	v_fma_f32 v25, v155, v17, 1.0
	v_xor_b32_e32 v18, 0x80000000, v24
	v_pk_mul_f32 v[20:21], v[24:25], v[20:21]
	v_pk_mul_f32 v[22:23], v[22:23], v[18:19]
	v_pk_mul_f32 v[16:17], v[16:17], v[20:21] op_sel_hi:[0,1]
	v_cvt_pk_bf16_f32 v18, v22, v23
	v_cvt_pk_bf16_f32 v16, v16, v17
	ds_write_b16 v75, v18
	ds_write_b16_d16_hi v75, v18 offset:2304
	ds_write_b16 v75, v16 offset:4608
	ds_write_b16_d16_hi v75, v16 offset:6912
	v_bfe_u32 v16, v30, 16, 1
	v_add3_u32 v16, v30, v16, s94
	ds_write_b16_d16_hi v75, v16 offset:9216
	s_waitcnt lgkmcnt(14)
	v_add_f32_e32 v16, v26, v27
	v_mul_f32_e32 v17, 0xbfb8aa3b, v16
	v_mul_f32_e32 v16, 0x3fb8aa3b, v16
	v_exp_f32_e32 v18, v16
	v_sub_f32_e32 v16, v29, v145
	v_fma_f32 v21, v139, v16, v145
	v_mul_f32_e32 v16, v154, v21
	v_mul_f32_e32 v20, v16, v16
	v_sub_f32_e32 v24, v28, v146
	v_exp_f32_e32 v17, v17
	v_mov_b32_dpp v20, v20 quad_perm:[1,0,3,2] row_mask:0xf bank_mask:0xf bound_ctrl:1
	v_fmac_f32_e32 v20, v16, v16
	s_nop 1
	v_add_f32_dpp v20, v20, v20 quad_perm:[2,3,0,1] row_mask:0xf bank_mask:0xf bound_ctrl:1
	s_nop 1
	v_add_f32_dpp v20, v20, v20 row_ror:4 row_mask:0xf bank_mask:0xf bound_ctrl:1
	s_nop 1
	v_add_f32_dpp v20, v20, v20 row_ror:8 row_mask:0xf bank_mask:0xf bound_ctrl:1
	s_nop 0
	v_readlane_b32 s3, v20, 16
	v_readlane_b32 s43, v20, 48
	v_readlane_b32 s0, v20, 0
	v_readlane_b32 s1, v20, 32
	v_mov_b32_e32 v22, s3
	v_mov_b32_e32 v23, s43
	v_pk_add_f32 v[22:23], s[0:1], v[22:23]
	s_nop 0
	v_add_f32_e32 v20, v22, v23
	v_rsq_f32_e32 v22, v20
	v_lshlrev_b32_e32 v20, 16, v202
	v_min_f32_e32 v22, 0x5368d4a5, v22
	v_fma_f32 v23, v51, v24, v146
	v_sub_f32_e32 v24, v31, v144
	v_fma_f32 v26, v156, v24, v144
	v_mul_f32_e32 v24, v16, v22
	v_mov_b32_e32 v22, v19
	v_add_f32_e32 v19, -1.0, v20
	v_fma_f32 v25, v155, v19, 1.0
	v_xor_b32_e32 v16, 0x80000000, v24
	v_pk_mul_f32 v[20:21], v[24:25], v[20:21]
	v_pk_mul_f32 v[22:23], v[22:23], v[16:17]
	v_pk_mul_f32 v[18:19], v[18:19], v[20:21] op_sel_hi:[0,1]
	v_cvt_pk_bf16_f32 v16, v22, v23
	v_cvt_pk_bf16_f32 v18, v18, v19
	ds_write_b16 v77, v16
	ds_write_b16_d16_hi v77, v16 offset:2304
	ds_write_b16 v77, v18 offset:4608
	ds_write_b16_d16_hi v77, v18 offset:6912
	v_bfe_u32 v16, v26, 16, 1
	v_cndmask_b32_e64 v18, 0, 1, s[38:39]
	v_add3_u32 v16, v26, v16, s94
	v_cmp_ne_u32_e64 s[44:45], 1, v18
	s_andn2_b64 vcc, exec, s[38:39]
	ds_write_b16_d16_hi v77, v16 offset:9216
	s_cbranch_vccnz .LBB0_843
	ds_write_b32 v65, v17 offset:13568

.LBB0_845:
	v_add_u32_e32 v30, 0x1000, v83
	s_waitcnt lgkmcnt(0)
	s_barrier
	ds_read2_b64 v[42:45], v83 offset1:4
	ds_read2_b64 v[224:227], v30 offset0:64 offset1:68
	v_add_u32_e32 v29, 0x800, v83
	ds_read2_b64 v[22:25], v29 offset0:32 offset1:36
	ds_read2_b64 v[228:231], v83 offset0:8 offset1:12
	ds_read2_b64 v[236:239], v30 offset0:72 offset1:76
	v_add_u32_e32 v40, 0x1800, v83
	ds_read2_b64 v[244:247], v40 offset0:96 offset1:100
	ds_read2_b64 v[32:35], v29 offset0:40 offset1:44
	s_waitcnt lgkmcnt(5)
	v_mfma_f32_16x16x32_bf16 v[232:235], v[42:45], v[224:227], 0
	v_cvt_pk_bf16_f32 v16, v4, v5
	v_cvt_pk_bf16_f32 v17, v6, v7
	v_cvt_pk_bf16_f32 v18, v0, v1
	v_mfma_f32_16x16x32_bf16 v[240:243], v[224:227], v[42:45], 0
	v_cvt_pk_bf16_f32 v19, v2, v3
	ds_read_u16 v20, v69 offset:9216
	ds_read_u16 v21, v69 offset:9360
	ds_read_u16 v26, v69 offset:9504
	v_cvt_pk_bf16_f32 v36, v8, v9
	s_waitcnt lgkmcnt(7)
	v_mfma_f32_16x16x32_bf16 v[224:227], v[224:227], v[22:25], 0
	v_cvt_pk_bf16_f32 v37, v10, v11
	s_waitcnt lgkmcnt(1)
	v_lshl_or_b32 v20, v21, 16, v20
	v_cvt_pk_bf16_f32 v38, v12, v13
	v_mfma_f32_16x16x32_bf16 v[232:235], v[228:231], v[236:239], v[232:235]
	v_cvt_pk_bf16_f32 v39, v14, v15
	v_add_u32_e32 v222, 0x3400, v81
	v_mfma_f32_16x16x32_bf16 v[240:243], v[236:239], v[228:231], v[240:243]
	v_mfma_f32_16x16x32_bf16 v[224:227], v[236:239], v[32:35], v[224:227]
	ds_read_u16 v27, v69 offset:9648
	ds_read2_b64 v[236:239], v40 offset0:104 offset1:108
	s_nop 4
	v_cndmask_b32_e64 v46, 0, v240, s[24:25]
	v_cndmask_b32_e64 v47, 0, v241, s[30:31]
	v_mfma_f32_16x16x32_bf16 v[148:151], v[22:25], v[16:19], 0
	s_waitcnt lgkmcnt(1)
	v_lshl_or_b32 v21, v27, 16, v26
	v_cndmask_b32_e64 v152, 0, v242, s[34:35]
	v_cndmask_b32_e64 v31, 0, v232, s[22:23]
	v_mfma_f32_16x16x32_bf16 v[16:19], v[42:45], v[16:19], 0
	v_cndmask_b32_e64 v41, v233, 0, s[24:25]
	v_mfma_f32_16x16x32_bf16 v[42:45], v[244:247], v[42:45], 0
	s_waitcnt lgkmcnt(0)
	v_mfma_f32_16x16x32_bf16 v[42:45], v[236:239], v[228:231], v[42:45]
	v_mfma_f32_16x16x32_bf16 v[16:19], v[228:231], v[36:39], v[16:19]
	v_mfma_f32_16x16x32_bf16 v[148:151], v[32:35], v[36:39], v[148:151]
	s_nop 5
	v_cndmask_b32_e64 v26, 0, v42, s[24:25]
	v_cndmask_b32_e64 v27, 0, v43, s[30:31]
	v_cndmask_b32_e64 v42, 0, v44, s[34:35]
	v_cndmask_b32_e64 v43, 0, v45, s[36:37]
	v_cvt_pk_bf16_f32 v26, v26, v27
	v_cvt_pk_bf16_f32 v27, v42, v43
	v_cndmask_b32_e64 v36, 0, v243, s[36:37]
	v_cvt_pk_bf16_f32 v42, v46, v47
	v_cvt_pk_bf16_f32 v43, v152, v36
	v_mfma_f32_16x16x16_bf16 v[16:19], v[26:27], v[20:21], v[16:19]
	v_cndmask_b32_e64 v36, 0, v234, s[26:27]
	s_nop 6
	v_cvt_pk_bf16_f32 v26, v16, v17
	v_cvt_pk_bf16_f32 v27, v18, v19
	s_nop 1
	v_mfma_f32_16x16x16_bf16 v[16:19], v[42:43], v[26:27], v[16:19]
	v_cndmask_b32_e64 v27, 0, v235, s[28:29]
	v_cvt_pk_bf16_f32 v26, v31, v41
	v_cvt_pk_bf16_f32 v27, v36, v27
	v_cndmask_b32_e64 v31, v224, 0, s[22:23]
	s_nop 0
	v_mfma_f32_16x16x16_bf16 v[36:39], v[42:43], v[26:27], 0
	v_mfma_f32_16x16x16_bf16 v[42:45], v[26:27], v[42:43], 0
	s_nop 7
	v_cvt_pk_bf16_f32 v26, v42, v43
	v_cvt_pk_bf16_f32 v27, v44, v45
	v_cvt_pk_bf16_f32 v42, v16, v17
	v_cvt_pk_bf16_f32 v43, v18, v19
	s_nop 1
	v_mfma_f32_16x16x16_bf16 v[16:19], v[26:27], v[42:43], v[16:19]
	v_cvt_pk_bf16_f32 v42, v36, v37
	v_cvt_pk_bf16_f32 v43, v38, v39
	s_nop 1
	v_mfma_f32_16x16x16_bf16 v[36:39], v[26:27], v[42:43], 0
	s_nop 7
	v_cvt_pk_bf16_f32 v44, v36, v37
	v_cvt_pk_bf16_f32 v45, v38, v39
	v_mfma_f32_16x16x16_bf16 v[36:39], v[42:43], v[26:27], 0
	v_cvt_pk_bf16_f32 v42, v16, v17
	v_cvt_pk_bf16_f32 v43, v18, v19
	s_nop 5
	v_cvt_pk_bf16_f32 v26, v36, v37
	v_cvt_pk_bf16_f32 v27, v38, v39
	s_nop 1
	v_mfma_f32_16x16x16_bf16 v[36:39], v[44:45], v[26:27], 0
	v_mfma_f32_16x16x16_bf16 v[16:19], v[26:27], v[42:43], v[16:19]
	s_nop 6
	v_cvt_pk_bf16_f32 v36, v36, v37
	v_cvt_pk_bf16_f32 v37, v38, v39
	v_cvt_pk_bf16_f32 v26, v16, v17
	v_cvt_pk_bf16_f32 v27, v18, v19
	v_cndmask_b32_e64 v38, v227, 0, s[28:29]
	s_nop 0
	v_mfma_f32_16x16x16_bf16 v[16:19], v[36:37], v[26:27], v[16:19]
	v_cndmask_b32_e64 v36, 0, v225, s[24:25]
	v_cndmask_b32_e64 v37, v226, 0, s[26:27]
	v_cvt_pk_bf16_f32 v36, v31, v36
	v_mfma_f32_16x16x32_bf16 v[24:27], v[244:247], v[22:25], 0
	v_cvt_pk_bf16_f32 v37, v37, v38
	s_nop 2
	v_cvt_pk_bf16_f32 v22, v16, v17
	v_cvt_pk_bf16_f32 v23, v18, v19
	v_mfma_f32_16x16x32_bf16 v[24:27], v[236:239], v[32:35], v[24:27]
	s_nop 0
	v_mfma_f32_16x16x16_bf16 v[16:19], v[36:37], v[22:23], v[148:151]
	s_nop 2
	v_add_u32_e32 v148, s2, v210
	s_nop 1
	v_cndmask_b32_e64 v24, v24, 0, s[22:23]
	v_cndmask_b32_e64 v25, 0, v25, s[24:25]
	v_cndmask_b32_e64 v26, v26, 0, s[26:27]
	v_cndmask_b32_e64 v27, v27, 0, s[28:29]
	v_cvt_pk_bf16_f32 v24, v24, v25
	v_cvt_pk_bf16_f32 v25, v26, v27
	v_ashrrev_i32_e32 v149, 31, v148
	s_nop 0
	v_mfma_f32_16x16x16_bf16 v[16:19], v[24:25], v[20:21], v[16:19]
	s_nop 7
	v_bfe_u32 v24, v16, 16, 1
	v_add3_u32 v16, v16, v24, s94
	v_lshlrev_b64 v[24:25], 10, v[148:149]
	v_lshl_add_u64 v[24:25], v[142:143], 0, v[24:25]
	global_store_short_d16_hi v[24:25], v16, off
	v_bfe_u32 v16, v17, 16, 1
	v_add3_u32 v24, v17, v16, s94
	v_add_u32_e32 v16, 1, v148
	v_ashrrev_i32_e32 v17, 31, v16
	v_lshlrev_b64 v[16:17], 10, v[16:17]
	v_lshl_add_u64 v[16:17], v[142:143], 0, v[16:17]
	global_store_short_d16_hi v[16:17], v24, off
	v_bfe_u32 v16, v18, 16, 1
	v_add3_u32 v18, v18, v16, s94
	v_add_u32_e32 v16, 2, v148
	v_ashrrev_i32_e32 v17, 31, v16
	v_lshlrev_b64 v[16:17], 10, v[16:17]
	v_lshl_add_u64 v[16:17], v[142:143], 0, v[16:17]
	global_store_short_d16_hi v[16:17], v18, off
	v_bfe_u32 v16, v19, 16, 1
	v_add3_u32 v26, v19, v16, s94
	v_add_u32_e32 v149, s33, v182
	ds_read_u16 v25, v79 offset:4752
	ds_read_b128 v[16:19], v149 offset:13568
	ds_read_u16 v27, v79 offset:4608
	ds_read2_b32 v[32:33], v222 offset0:64 offset1:80
	v_add_u32_e32 v24, 3, v148
	s_waitcnt lgkmcnt(3)
	v_lshlrev_b32_e32 v35, 16, v25
	ds_read_u16 v25, v79 offset:5040
	ds_read_u16 v31, v79 offset:4896
	s_waitcnt lgkmcnt(3)
	v_lshlrev_b32_e32 v34, 16, v27
	v_pk_mul_f32 v[4:5], v[4:5], v[16:17]
	ds_read_u16 v16, v79 offset:6912
	s_waitcnt lgkmcnt(2)
	v_lshlrev_b32_e32 v37, 16, v25
	s_waitcnt lgkmcnt(1)
	v_lshlrev_b32_e32 v36, 16, v31
	ds_read_u16 v25, v79 offset:7056
	v_pk_mul_f32 v[34:35], v[32:33], v[34:35] op_sel_hi:[0,1]
	v_pk_mul_f32 v[36:37], v[32:33], v[36:37] op_sel_hi:[0,1]
	v_cvt_pk_bf16_f32 v34, v34, v35
	v_cvt_pk_bf16_f32 v35, v36, v37
	v_pk_mul_f32 v[6:7], v[6:7], v[18:19]
	ds_read_u16 v18, v79 offset:7344
	ds_read_u16 v19, v79 offset:7200
	s_waitcnt lgkmcnt(2)
	v_lshlrev_b32_e32 v17, 16, v25
	v_lshlrev_b32_e32 v16, 16, v16
	v_pk_mul_f32 v[16:17], v[32:33], v[16:17] op_sel_hi:[0,1]
	v_mfma_f32_16x16x16_bf16 v[4:7], v[34:35], v[22:23], v[4:7]
	v_cvt_pk_bf16_f32 v34, v16, v17
	s_waitcnt lgkmcnt(1)
	v_lshlrev_b32_e32 v17, 16, v18
	s_waitcnt lgkmcnt(0)
	v_lshlrev_b32_e32 v16, 16, v19
	v_pk_mul_f32 v[16:17], v[32:33], v[16:17] op_sel_hi:[0,1]
	v_cvt_pk_bf16_f32 v35, v16, v17
	ds_read_b128 v[16:19], v149 offset:13632
	ds_read_u16 v27, v79 offset:4784
	ds_read_u16 v31, v79 offset:4640
	v_ashrrev_i32_e32 v25, 31, v24
	v_mfma_f32_16x16x16_bf16 v[4:7], v[34:35], v[20:21], v[4:7]
	s_waitcnt lgkmcnt(2)
	v_pk_mul_f32 v[2:3], v[2:3], v[18:19]
	ds_read_u16 v19, v79 offset:5072
	v_pk_mul_f32 v[0:1], v[0:1], v[16:17]
	s_waitcnt lgkmcnt(2)
	v_lshlrev_b32_e32 v17, 16, v27
	s_waitcnt lgkmcnt(1)
	v_lshlrev_b32_e32 v16, 16, v31
	v_mov_b32_e32 v18, v33
	ds_read_u16 v27, v79 offset:4928
	s_waitcnt lgkmcnt(1)
	v_pk_mul_f32 v[16:17], v[18:19], v[16:17] op_sel_hi:[0,1]
	v_lshlrev_b32_e32 v33, 16, v19
	ds_read_u16 v19, v79 offset:7088
	v_cvt_pk_bf16_f32 v16, v16, v17
	s_waitcnt lgkmcnt(1)
	v_lshlrev_b32_e32 v32, 16, v27
	ds_read_u16 v27, v79 offset:6944
	s_waitcnt lgkmcnt(1)
	v_pk_mul_f32 v[32:33], v[18:19], v[32:33] op_sel_hi:[0,1]
	v_cvt_pk_bf16_f32 v17, v32, v33
	v_lshlrev_b32_e32 v33, 16, v19
	ds_read_u16 v19, v79 offset:7376
	ds_read_u16 v31, v79 offset:7232
	s_waitcnt lgkmcnt(2)
	v_lshlrev_b32_e32 v32, 16, v27
	v_mfma_f32_16x16x16_bf16 v[0:3], v[16:17], v[22:23], v[0:3]
	s_waitcnt lgkmcnt(1)
	v_pk_mul_f32 v[32:33], v[18:19], v[32:33] op_sel_hi:[0,1]
	v_cvt_pk_bf16_f32 v36, v32, v33
	v_lshlrev_b32_e32 v33, 16, v19
	s_waitcnt lgkmcnt(0)
	v_lshlrev_b32_e32 v32, 16, v31
	v_pk_mul_f32 v[18:19], v[18:19], v[32:33] op_sel_hi:[0,1]
	v_cvt_pk_bf16_f32 v37, v18, v19
	v_lshlrev_b64 v[16:17], 10, v[24:25]
	ds_read_b128 v[32:35], v149 offset:13696
	ds_read_u16 v18, v79 offset:4816
	ds_read2_b32 v[24:25], v222 offset0:96 offset1:112
	ds_read_u16 v27, v79 offset:4672
	ds_read_u16 v31, v79 offset:5104
	v_lshl_add_u64 v[16:17], v[142:143], 0, v[16:17]
	s_waitcnt lgkmcnt(3)
	v_lshlrev_b32_e32 v19, 16, v18
	v_pk_mul_f32 v[8:9], v[8:9], v[32:33]
	s_waitcnt lgkmcnt(1)
	v_lshlrev_b32_e32 v18, 16, v27
	ds_read_u16 v27, v79 offset:4960
	s_waitcnt lgkmcnt(1)
	v_lshlrev_b32_e32 v33, 16, v31
	ds_read_u16 v31, v79 offset:7120
	v_pk_mul_f32 v[18:19], v[24:25], v[18:19] op_sel_hi:[0,1]
	v_pk_mul_f32 v[10:11], v[10:11], v[34:35]
	s_waitcnt lgkmcnt(1)
	v_lshlrev_b32_e32 v32, 16, v27
	v_pk_mul_f32 v[32:33], v[24:25], v[32:33] op_sel_hi:[0,1]
	v_cvt_pk_bf16_f32 v18, v18, v19
	ds_read_u16 v27, v79 offset:6976
	v_cvt_pk_bf16_f32 v19, v32, v33
	s_waitcnt lgkmcnt(1)
	v_lshlrev_b32_e32 v33, 16, v31
	ds_read_u16 v31, v79 offset:7408
	ds_read_u16 v34, v79 offset:7264
	v_mfma_f32_16x16x16_bf16 v[8:11], v[18:19], v[22:23], v[8:11]
	s_waitcnt lgkmcnt(2)
	v_lshlrev_b32_e32 v32, 16, v27
	s_waitcnt lgkmcnt(1)
	v_lshlrev_b32_e32 v35, 16, v31
	s_waitcnt lgkmcnt(0)
	v_lshlrev_b32_e32 v34, 16, v34
	v_pk_mul_f32 v[32:33], v[24:25], v[32:33] op_sel_hi:[0,1]
	v_pk_mul_f32 v[34:35], v[24:25], v[34:35] op_sel_hi:[0,1]
	v_cvt_pk_bf16_f32 v32, v32, v33
	v_cvt_pk_bf16_f32 v33, v34, v35
	ds_read_u16 v24, v79 offset:4848
	ds_read_u16 v31, v79 offset:4704
	global_store_short_d16_hi v[16:17], v26, off
	v_mfma_f32_16x16x16_bf16 v[8:11], v[32:33], v[20:21], v[8:11]
	ds_read_b128 v[16:19], v149 offset:13760
	s_waitcnt lgkmcnt(1)
	v_lshlrev_b32_e32 v26, 16, v31
	ds_read_u16 v31, v79 offset:5136
	ds_read_u16 v32, v79 offset:4992
	v_lshlrev_b32_e32 v27, 16, v24
	v_mov_b32_e32 v24, v25
	v_pk_mul_f32 v[26:27], v[24:25], v[26:27] op_sel_hi:[0,1]
	s_waitcnt lgkmcnt(1)
	v_lshlrev_b32_e32 v33, 16, v31
	s_waitcnt lgkmcnt(0)
	v_lshlrev_b32_e32 v32, 16, v32
	v_pk_mul_f32 v[32:33], v[24:25], v[32:33] op_sel_hi:[0,1]
	v_cvt_pk_bf16_f32 v26, v26, v27
	v_cvt_pk_bf16_f32 v27, v32, v33
	v_pk_mul_f32 v[12:13], v[12:13], v[16:17]
	v_pk_mul_f32 v[14:15], v[14:15], v[18:19]
	ds_read_u16 v25, v79 offset:7152
	ds_read_u16 v16, v79 offset:7008
	v_mfma_f32_16x16x16_bf16 v[12:15], v[26:27], v[22:23], v[12:15]
	ds_read_u16 v18, v79 offset:7440
	ds_read_u16 v22, v79 offset:7296
	v_lshlrev_b32_e32 v27, 16, v191
	s_waitcnt lgkmcnt(3)
	v_lshlrev_b32_e32 v17, 16, v25
	s_waitcnt lgkmcnt(2)
	v_lshlrev_b32_e32 v16, 16, v16
	s_waitcnt lgkmcnt(1)
	v_lshlrev_b32_e32 v19, 16, v18
	s_waitcnt lgkmcnt(0)
	v_lshlrev_b32_e32 v18, 16, v22
	v_pk_mul_f32 v[16:17], v[24:25], v[16:17] op_sel_hi:[0,1]
	v_pk_mul_f32 v[18:19], v[24:25], v[18:19] op_sel_hi:[0,1]
	v_cvt_pk_bf16_f32 v16, v16, v17
	v_cvt_pk_bf16_f32 v17, v18, v19
	v_lshlrev_b32_e32 v18, 16, v196
	ds_write_b32 v203, v18 offset:17920
	v_add_f32_e32 v18, 0, v18
	v_lshlrev_b32_e32 v19, 16, v205
	ds_write_b32 v204, v19 offset:17920
	v_add_f32_e32 v18, v18, v19
	v_lshlrev_b32_e32 v19, 16, v215
	ds_write_b32 v207, v19 offset:17920
	v_add_f32_e32 v18, v18, v19
	s_waitcnt vmcnt(5)
	v_lshlrev_b32_e32 v19, 16, v218
	v_add_f32_e32 v18, v18, v19
	ds_write_b32 v211, v19 offset:17920
	ds_write_b32 v67, v18 offset:24064
	s_waitcnt lgkmcnt(0)
	s_barrier
	ds_read2st64_b32 v[18:19], v65 offset0:94 offset1:95
	v_mfma_f32_16x16x16_bf16 v[12:15], v[16:17], v[20:21], v[12:15]
	ds_read_b32 v17, v65 offset:24576
	v_lshlrev_b32_e32 v26, 16, v190
	v_lshlrev_b32_e32 v31, 16, v192
	s_waitcnt lgkmcnt(1)
	v_add_f32_e32 v16, 0, v18
	v_cndmask_b32_e64 v18, 0, v19, s[40:41]
	ds_read_b32 v19, v203 offset:17920
	v_cndmask_b32_e64 v16, v16, 0, s[84:85]
	v_add_f32_e32 v16, v16, v18
	s_waitcnt lgkmcnt(1)
	v_cndmask_b32_e64 v17, 0, v17, s[38:39]
	v_add_f32_e32 v16, v16, v17
	v_mfma_f32_16x16x16_bf16 v[0:3], v[36:37], v[20:21], v[0:3]
	s_waitcnt lgkmcnt(0)
	v_add_f32_e32 v21, v19, v16
	v_mul_f32_e32 v17, 0xbfb8aa3b, v16
	v_mul_f32_e32 v16, 0xbfb8aa3b, v21
	v_exp_f32_e32 v18, v17
	v_exp_f32_e32 v17, v16
	v_mul_f32_e32 v16, 0x3fb8aa3b, v21
	v_exp_f32_e32 v20, v16
	v_sub_f32_e32 v16, v49, v27
	v_fma_f32 v23, v139, v16, v27
	v_mul_f32_e32 v16, v154, v23
	v_mul_f32_e32 v19, v16, v16
	v_lshlrev_b32_e32 v34, 16, v198
	v_lshlrev_b32_e32 v35, 16, v201
	v_mov_b32_dpp v19, v19 quad_perm:[1,0,3,2] row_mask:0xf bank_mask:0xf bound_ctrl:1
	v_fmac_f32_e32 v19, v16, v16
	v_and_b32_e32 v49, 0xffff0000, v220
	s_nop 0
	v_add_f32_dpp v19, v19, v19 quad_perm:[2,3,0,1] row_mask:0xf bank_mask:0xf bound_ctrl:1
	s_nop 1
	v_add_f32_dpp v19, v19, v19 row_ror:4 row_mask:0xf bank_mask:0xf bound_ctrl:1
	s_nop 1
	v_add_f32_dpp v19, v19, v19 row_ror:8 row_mask:0xf bank_mask:0xf bound_ctrl:1
	s_nop 0
	v_readlane_b32 s3, v19, 16
	v_readlane_b32 s43, v19, 48
	v_readlane_b32 s0, v19, 0
	v_readlane_b32 s1, v19, 32
	v_mov_b32_e32 v24, s3
	v_mov_b32_e32 v25, s43
	v_pk_add_f32 v[24:25], s[0:1], v[24:25]
	s_nop 0
	v_add_f32_e32 v19, v24, v25
	v_sub_f32_e32 v25, v223, v26
	v_rsq_f32_e32 v19, v19
	v_lshlrev_b32_e32 v22, 16, v197
	v_lshlrev_b32_e32 v223, 16, v217
	v_lshlrev_b32_e32 v33, 16, v199
	s_nop 0
	v_min_f32_e32 v24, 0x5368d4a5, v19
	v_fma_f32 v19, v51, v25, v26
	v_sub_f32_e32 v25, v56, v31
	v_fma_f32 v32, v156, v25, v31
	v_mul_f32_e32 v24, v16, v24
	v_xor_b32_e32 v16, 0x80000000, v24
	v_pk_mul_f32 v[18:19], v[18:19], v[16:17]
	v_lshlrev_b32_e32 v56, 16, v220
	v_cvt_pk_bf16_f32 v16, v18, v19
	v_add_f32_e32 v18, -1.0, v22
	v_fma_f32 v25, v155, v18, 1.0
	v_pk_mul_f32 v[18:19], v[24:25], v[22:23]
	v_sub_f32_e32 v24, v26, v34
	v_pk_mul_f32 v[18:19], v[20:21], v[18:19] op_sel_hi:[0,1]
	v_cvt_pk_bf16_f32 v18, v18, v19
	ds_write_b16 v71, v16
	ds_write_b16_d16_hi v71, v16 offset:2304
	ds_write_b16 v71, v18 offset:4608
	ds_read_b32 v16, v204 offset:17920
	ds_write_b16_d16_hi v71, v18 offset:6912
	v_bfe_u32 v18, v32, 16, 1
	v_add3_u32 v18, v32, v18, s94
	ds_write_b16_d16_hi v71, v18 offset:9216
	v_sub_f32_e32 v18, v27, v33
	s_waitcnt lgkmcnt(2)
	v_add_f32_e32 v32, v21, v16
	v_fma_f32 v21, v139, v18, v33
	v_mul_f32_e32 v18, v154, v21
	v_mul_f32_e32 v20, v18, v18
	v_mul_f32_e32 v16, 0xbfb8aa3b, v32
	v_exp_f32_e32 v19, v16
	v_mov_b32_dpp v20, v20 quad_perm:[1,0,3,2] row_mask:0xf bank_mask:0xf bound_ctrl:1
	v_fmac_f32_e32 v20, v18, v18
	v_mul_f32_e32 v16, 0x3fb8aa3b, v32
	v_exp_f32_e32 v16, v16
	v_add_f32_dpp v20, v20, v20 quad_perm:[2,3,0,1] row_mask:0xf bank_mask:0xf bound_ctrl:1
	s_nop 1
	v_add_f32_dpp v20, v20, v20 row_ror:4 row_mask:0xf bank_mask:0xf bound_ctrl:1
	s_nop 1
	v_add_f32_dpp v20, v20, v20 row_ror:8 row_mask:0xf bank_mask:0xf bound_ctrl:1
	s_nop 0
	v_readlane_b32 s3, v20, 16
	v_readlane_b32 s43, v20, 48
	v_readlane_b32 s0, v20, 0
	v_readlane_b32 s1, v20, 32
	v_mov_b32_e32 v22, s3
	v_mov_b32_e32 v23, s43
	v_pk_add_f32 v[22:23], s[0:1], v[22:23]
	s_nop 0
	v_add_f32_e32 v20, v22, v23
	v_rsq_f32_e32 v22, v20
	v_lshlrev_b32_e32 v20, 16, v206
	v_min_f32_e32 v22, 0x5368d4a5, v22
	v_fma_f32 v23, v51, v24, v34
	v_sub_f32_e32 v24, v31, v35
	v_fma_f32 v26, v156, v24, v35
	v_mul_f32_e32 v24, v18, v22
	v_mov_b32_e32 v22, v17
	v_add_f32_e32 v17, -1.0, v20
	v_xor_b32_e32 v18, 0x80000000, v24
	v_fma_f32 v25, v155, v17, 1.0
	v_pk_mul_f32 v[22:23], v[22:23], v[18:19]
	v_pk_mul_f32 v[20:21], v[24:25], v[20:21]
	v_cvt_pk_bf16_f32 v18, v22, v23
	v_pk_mul_f32 v[16:17], v[16:17], v[20:21] op_sel_hi:[0,1]
	v_cvt_pk_bf16_f32 v16, v16, v17
	ds_write_b16 v73, v18
	ds_write_b16_d16_hi v73, v18 offset:2304
	ds_write_b16 v73, v16 offset:4608
	ds_read_b32 v17, v207 offset:17920
	ds_write_b16_d16_hi v73, v16 offset:6912
	v_bfe_u32 v16, v26, 16, 1
	v_add3_u32 v16, v26, v16, s94
	ds_write_b16_d16_hi v73, v16 offset:9216
	s_waitcnt lgkmcnt(2)
	v_add_f32_e32 v22, v32, v17
	v_mul_f32_e32 v16, 0xbfb8aa3b, v22
	v_exp_f32_e32 v17, v16
	v_mul_f32_e32 v16, 0x3fb8aa3b, v22
	v_lshlrev_b32_e32 v21, 16, v213
	v_exp_f32_e32 v24, v16
	v_sub_f32_e32 v16, v33, v21
	v_fma_f32 v27, v139, v16, v21
	v_mul_f32_e32 v16, v154, v27
	v_mul_f32_e32 v20, v16, v16
	v_lshlrev_b32_e32 v18, 16, v212
	v_sub_f32_e32 v31, v34, v18
	v_mov_b32_dpp v20, v20 quad_perm:[1,0,3,2] row_mask:0xf bank_mask:0xf bound_ctrl:1
	v_fmac_f32_e32 v20, v16, v16
	v_lshlrev_b32_e32 v26, 16, v216
	v_sub_f32_e32 v21, v21, v49
	v_add_f32_dpp v20, v20, v20 quad_perm:[2,3,0,1] row_mask:0xf bank_mask:0xf bound_ctrl:1
	s_nop 1
	v_add_f32_dpp v20, v20, v20 row_ror:4 row_mask:0xf bank_mask:0xf bound_ctrl:1
	s_nop 1
	v_add_f32_dpp v20, v20, v20 row_ror:8 row_mask:0xf bank_mask:0xf bound_ctrl:1
	s_nop 0
	v_readlane_b32 s3, v20, 16
	v_readlane_b32 s43, v20, 48
	v_readlane_b32 s0, v20, 0
	v_readlane_b32 s1, v20, 32
	v_mov_b32_e32 v32, s3
	v_mov_b32_e32 v33, s43
	v_pk_add_f32 v[32:33], s[0:1], v[32:33]
	s_nop 0
	v_add_f32_e32 v20, v32, v33
	v_rsq_f32_e32 v23, v20
	v_lshlrev_b32_e32 v20, 16, v214
	v_fma_f32 v33, v51, v31, v18
	v_mov_b32_e32 v32, v19
	v_min_f32_e32 v25, 0x5368d4a5, v23
	v_sub_f32_e32 v23, v35, v20
	v_fma_f32 v23, v156, v23, v20
	v_sub_f32_e32 v18, v18, v223
	v_mul_f32_e32 v34, v16, v25
	v_xor_b32_e32 v16, 0x80000000, v34
	v_pk_mul_f32 v[32:33], v[32:33], v[16:17]
	v_add_f32_e32 v16, -1.0, v26
	v_fma_f32 v35, v155, v16, 1.0
	v_pk_mul_f32 v[26:27], v[34:35], v[26:27]
	v_cvt_pk_bf16_f32 v19, v32, v33
	v_pk_mul_f32 v[24:25], v[24:25], v[26:27] op_sel_hi:[0,1]
	v_cvt_pk_bf16_f32 v16, v24, v25
	ds_write_b16 v75, v19
	ds_write_b16_d16_hi v75, v19 offset:2304
	ds_write_b16 v75, v16 offset:4608
	ds_write_b16_d16_hi v75, v16 offset:6912
	v_bfe_u32 v16, v23, 16, 1
	v_add3_u32 v16, v23, v16, s94
	v_fma_f32 v23, v139, v21, v49
	v_mul_f32_e32 v26, v154, v23
	v_mul_f32_e32 v21, v26, v26
	ds_read_b32 v19, v211 offset:17920
	ds_write_b16_d16_hi v75, v16 offset:9216
	v_mov_b32_dpp v21, v21 quad_perm:[1,0,3,2] row_mask:0xf bank_mask:0xf bound_ctrl:1
	v_fmac_f32_e32 v21, v26, v26
	s_waitcnt lgkmcnt(1)
	v_add_f32_e32 v16, v22, v19
	v_add_f32_dpp v21, v21, v21 quad_perm:[2,3,0,1] row_mask:0xf bank_mask:0xf bound_ctrl:1
	v_mul_f32_e32 v19, 0xbfb8aa3b, v16
	v_exp_f32_e32 v19, v19
	v_add_f32_dpp v21, v21, v21 row_ror:4 row_mask:0xf bank_mask:0xf bound_ctrl:1
	v_mul_f32_e32 v16, 0x3fb8aa3b, v16
	v_exp_f32_e32 v16, v16
	v_add_f32_dpp v21, v21, v21 row_ror:8 row_mask:0xf bank_mask:0xf bound_ctrl:1
	s_nop 0
	v_readlane_b32 s3, v21, 16
	v_readlane_b32 s43, v21, 48
	v_readlane_b32 s0, v21, 0
	v_readlane_b32 s1, v21, 32
	v_mov_b32_e32 v24, s3
	v_mov_b32_e32 v25, s43
	v_pk_add_f32 v[24:25], s[0:1], v[24:25]
	s_nop 0
	v_add_f32_e32 v21, v24, v25
	v_rsq_f32_e32 v21, v21
	s_waitcnt vmcnt(4)
	v_lshlrev_b32_e32 v22, 16, v219
	v_min_f32_e32 v24, 0x5368d4a5, v21
	v_fma_f32 v21, v51, v18, v223
	v_sub_f32_e32 v18, v20, v56
	v_fma_f32 v27, v156, v18, v56
	v_mul_f32_e32 v24, v26, v24
	v_xor_b32_e32 v18, 0x80000000, v24
	v_mov_b32_e32 v20, v17
	v_add_f32_e32 v17, -1.0, v22
	v_pk_mul_f32 v[20:21], v[20:21], v[18:19]
	v_fma_f32 v25, v155, v17, 1.0
	v_cvt_pk_bf16_f32 v18, v20, v21
	v_pk_mul_f32 v[20:21], v[24:25], v[22:23]
	s_and_b64 vcc, exec, s[44:45]
	v_pk_mul_f32 v[16:17], v[16:17], v[20:21] op_sel_hi:[0,1]
	v_cvt_pk_bf16_f32 v16, v16, v17
	ds_write_b16 v77, v18
	ds_write_b16_d16_hi v77, v18 offset:2304
	ds_write_b16 v77, v16 offset:4608
	ds_write_b16_d16_hi v77, v16 offset:6912
	v_bfe_u32 v16, v27, 16, 1
	v_add3_u32 v16, v27, v16, s94
	ds_write_b16_d16_hi v77, v16 offset:9216
	s_cbranch_vccnz .LBB0_847
	ds_write_b32 v65, v19 offset:13568
